# gla_inter epilogue: all 16 gain/gate loads of a unit in flight at once (was 8 load-wait-compute-store steps)
# speedup vs baseline: 1.0411x; 1.0035x over previous
; __device__ __forceinline__ unsigned pk2(float lo, float hi) { return pg8::cvtpk(lo, hi); }
; __device__ __forceinline__ float silu_f(float v) { return v * __builtin_amdgcn_rcpf(1.0f + __expf(-v)); }
; __device__ __forceinline__ void gla_inter_unit(const Params& P, LAS unsigned char* lds, int unit) {
;     ...
;     const float tot = red[cb * 16 + fr] + red[(cb + 4) * 16 + fr];
;     const float rstd = rsqrtf(tot * (1.0f / 256.0f) + RMS_EPS);
; #pragma unroll
;     for (int vbi = 0; vbi < 8; ++vbi) { const int vcol = 16 * (vh * 8 + vbi) + 4 * fq;
;         const f32x4 g = *(const f32x4*)(P.g_gla + vcol); const u32x2 rw = *(const u32x2*)(Z + trow * ZC + ZO_RG + 256 * h + vcol);
;         const float r0 = __uint_as_float(rw.x << 16), r1 = __uint_as_float(rw.x & 0xffff0000u), r2 = __uint_as_float(rw.y << 16), r3 = __uint_as_float(rw.y & 0xffff0000u);
;         u32x2 w; w.x = pk2(o[vbi][0] * rstd * g[0] * silu_f(r0), o[vbi][1] * rstd * g[1] * silu_f(r1)); w.y = pk2(o[vbi][2] * rstd * g[2] * silu_f(r2), o[vbi][3] * rstd * g[3] * silu_f(r3));
;         *(u32x2*)(AO + trow * DM + 1024 + 256 * h + vcol) = w; }
.LBB0_542:
	s_or_b64 exec, exec, s[22:23]
	v_lshlrev_b32_e32 v5, 2, v55
	v_add3_u32 v4, 0, v5, v4
	s_waitcnt lgkmcnt(0)
	s_barrier
	ds_read2st64_b32 v[4:5], v4 offset1:1
	s_mov_b32 s22, 0x800000
	v_lshlrev_b32_e32 v8, 2, v53
	v_or_b32_e32 v10, v8, v40
	v_lshlrev_b64 v[8:9], 13, v[42:43]
	s_waitcnt lgkmcnt(0)
	v_add_f32_e32 v4, v4, v5
	v_fmamk_f32 v4, v4, 0x3b800000, v52
	v_cmp_gt_f32_e32 vcc, s22, v4
	v_mul_f32_e32 v5, 0x4b800000, v4
	v_lshl_add_u64 v[8:9], s[56:57], 0, v[8:9]
	v_cndmask_b32_e32 v4, v4, v5, vcc
	v_rsq_f32_e32 v4, v4
	v_ashrrev_i32_e32 v11, 31, v10
	v_lshl_add_u64 v[12:13], v[8:9], 0, s[68:69]
	v_lshlrev_b64 v[8:9], 12, v[42:43]
	v_lshlrev_b64 v[56:57], 1, v[10:11]
	v_lshl_add_u64 v[8:9], s[58:59], 0, v[8:9]
	v_lshl_add_u64 v[12:13], v[12:13], 0, v[56:57]
	s_mov_b64 s[22:23], 0x1600
	v_mul_f32_e32 v5, 0x45800000, v4
	v_lshl_add_u64 v[54:55], v[8:9], 0, s[68:69]
	v_lshl_add_u64 v[8:9], v[10:11], 2, s[90:91]
	v_lshl_add_u64 v[10:11], v[12:13], 0, s[22:23]
	s_movk_i32 s22, 0x1000
	v_cndmask_b32_e32 v4, v4, v5, vcc
	v_add_co_u32_e32 v12, vcc, s22, v12
	s_nop 0
	v_addc_co_u32_e32 v13, vcc, 0, v13, vcc
	global_load_dwordx4 v[60:63], v[8:9], off
	global_load_dwordx2 v[92:93], v[12:13], off offset:1536
	global_load_dwordx4 v[64:67], v[8:9], off offset:64
	global_load_dwordx2 v[94:95], v[10:11], off offset:32
	global_load_dwordx4 v[68:71], v[8:9], off offset:128
	global_load_dwordx2 v[96:97], v[10:11], off offset:64
	global_load_dwordx4 v[72:75], v[8:9], off offset:192
	global_load_dwordx2 v[98:99], v[10:11], off offset:96
	global_load_dwordx4 v[76:79], v[8:9], off offset:256
	global_load_dwordx2 v[100:101], v[10:11], off offset:128
	global_load_dwordx4 v[80:83], v[8:9], off offset:320
	global_load_dwordx2 v[102:103], v[10:11], off offset:160
	global_load_dwordx4 v[84:87], v[8:9], off offset:384
	global_load_dwordx2 v[104:105], v[10:11], off offset:192
	global_load_dwordx4 v[88:91], v[8:9], off offset:448
	global_load_dwordx2 v[106:107], v[10:11], off offset:224
	s_mov_b64 s[22:23], 0x6800800
	s_add_i32 s27, s27, s92
	s_add_u32 s52, s52, s54
	s_addc_u32 s53, s53, s55
	s_add_u32 s38, s38, s40
	s_addc_u32 s39, s39, s41
	s_add_i32 s3, s3, s26
	s_cmpk_gt_i32 s27, 0x3ff
	s_waitcnt vmcnt(14)
	v_mov_b32_e32 v40, v60
	v_mov_b32_e32 v41, v61
	v_mov_b32_e32 v42, v62
	v_mov_b32_e32 v43, v63
	v_mov_b32_e32 v12, v92
	v_mov_b32_e32 v13, v93
	v_lshlrev_b32_e32 v14, 16, v12
	v_mul_f32_e32 v5, 0xbfb8aa3b, v14
	v_exp_f32_e32 v5, v5
	v_and_b32_e32 v15, 0xffff0000, v12
	v_lshlrev_b32_e32 v12, 16, v13
	v_and_b32_e32 v13, 0xffff0000, v13
	v_add_f32_e32 v5, 1.0, v5
	v_rcp_f32_e32 v58, v5
	v_pk_mul_f32 v[46:47], v[46:47], v[4:5] op_sel_hi:[1,0]
	v_mul_f32_e32 v5, 0xbfb8aa3b, v15
	v_exp_f32_e32 v5, v5
	v_pk_mul_f32 v[40:41], v[40:41], v[46:47]
	v_add_f32_e32 v5, 1.0, v5
	v_rcp_f32_e32 v59, v5
	v_mul_f32_e32 v5, 0xbfb8aa3b, v12
	v_exp_f32_e32 v5, v5
	v_pk_mul_f32 v[14:15], v[58:59], v[14:15]
	s_nop 0
	v_pk_mul_f32 v[14:15], v[40:41], v[14:15]
	v_add_f32_e32 v5, 1.0, v5
	v_rcp_f32_e32 v40, v5
	v_pk_mul_f32 v[44:45], v[44:45], v[4:5] op_sel_hi:[1,0]
	v_mul_f32_e32 v5, 0xbfb8aa3b, v13
	v_exp_f32_e32 v5, v5
	v_pk_mul_f32 v[42:43], v[42:43], v[44:45]
	v_cvt_pk_bf16_f32 v14, v14, v15
	v_add_f32_e32 v5, 1.0, v5
	v_rcp_f32_e32 v41, v5
	s_nop 0
	v_pk_mul_f32 v[12:13], v[40:41], v[12:13]
	s_nop 0
	v_pk_mul_f32 v[12:13], v[42:43], v[12:13]
	v_lshl_add_u64 v[40:41], v[54:55], 0, v[56:57]
	v_cvt_pk_bf16_f32 v15, v12, v13
	v_lshl_add_u64 v[12:13], v[40:41], 0, s[22:23]
	s_mov_b32 s22, 0x6800000
	v_add_co_u32_e32 v40, vcc, s22, v40
	s_nop 1
	v_addc_co_u32_e32 v41, vcc, 0, v41, vcc
	global_store_dwordx2 v[40:41], v[14:15], off offset:2048
	s_nop 0
	s_waitcnt vmcnt(13)
	v_mov_b32_e32 v40, v64
	v_mov_b32_e32 v41, v65
	v_mov_b32_e32 v42, v66
	v_mov_b32_e32 v43, v67
	v_mov_b32_e32 v14, v94
	v_mov_b32_e32 v15, v95
	v_lshlrev_b32_e32 v44, 16, v14
	v_mul_f32_e32 v5, 0xbfb8aa3b, v44
	v_exp_f32_e32 v5, v5
	v_and_b32_e32 v45, 0xffff0000, v14
	v_add_f32_e32 v5, 1.0, v5
	v_rcp_f32_e32 v46, v5
	v_pk_mul_f32 v[38:39], v[38:39], v[4:5] op_sel_hi:[1,0]
	v_mul_f32_e32 v5, 0xbfb8aa3b, v45
	v_exp_f32_e32 v5, v5
	v_pk_mul_f32 v[38:39], v[40:41], v[38:39]
	v_add_f32_e32 v5, 1.0, v5
	v_rcp_f32_e32 v47, v5
	s_nop 0
	v_pk_mul_f32 v[40:41], v[46:47], v[44:45]
	s_nop 0
	v_pk_mul_f32 v[38:39], v[38:39], v[40:41]
	s_nop 0
	v_cvt_pk_bf16_f32 v14, v38, v39
	v_lshlrev_b32_e32 v38, 16, v15
	v_mul_f32_e32 v5, 0xbfb8aa3b, v38
	v_exp_f32_e32 v5, v5
	v_and_b32_e32 v39, 0xffff0000, v15
	v_add_f32_e32 v5, 1.0, v5
	v_rcp_f32_e32 v40, v5
	v_pk_mul_f32 v[36:37], v[36:37], v[4:5] op_sel_hi:[1,0]
	v_mul_f32_e32 v5, 0xbfb8aa3b, v39
	v_exp_f32_e32 v5, v5
	v_pk_mul_f32 v[36:37], v[42:43], v[36:37]
	v_add_f32_e32 v5, 1.0, v5
	v_rcp_f32_e32 v41, v5
	s_nop 0
	v_pk_mul_f32 v[38:39], v[40:41], v[38:39]
	s_nop 0
	v_pk_mul_f32 v[36:37], v[36:37], v[38:39]
	s_nop 0
	v_cvt_pk_bf16_f32 v15, v36, v37
	global_store_dwordx2 v[12:13], v[14:15], off offset:32
	s_nop 0
	s_waitcnt vmcnt(12)
	v_mov_b32_e32 v36, v68
	v_mov_b32_e32 v37, v69
	v_mov_b32_e32 v38, v70
	v_mov_b32_e32 v39, v71
	v_mov_b32_e32 v14, v96
	v_mov_b32_e32 v15, v97
	v_lshlrev_b32_e32 v40, 16, v14
	v_mul_f32_e32 v5, 0xbfb8aa3b, v40
	v_exp_f32_e32 v5, v5
	v_and_b32_e32 v41, 0xffff0000, v14
	v_add_f32_e32 v5, 1.0, v5
	v_rcp_f32_e32 v42, v5
	v_pk_mul_f32 v[34:35], v[34:35], v[4:5] op_sel_hi:[1,0]
	v_mul_f32_e32 v5, 0xbfb8aa3b, v41
	v_exp_f32_e32 v5, v5
	v_pk_mul_f32 v[34:35], v[36:37], v[34:35]
	v_add_f32_e32 v5, 1.0, v5
	v_rcp_f32_e32 v43, v5
	s_nop 0
	v_pk_mul_f32 v[36:37], v[42:43], v[40:41]
	s_nop 0
	v_pk_mul_f32 v[34:35], v[34:35], v[36:37]
	s_nop 0
	v_cvt_pk_bf16_f32 v14, v34, v35
	v_lshlrev_b32_e32 v34, 16, v15
	v_mul_f32_e32 v5, 0xbfb8aa3b, v34
	v_exp_f32_e32 v5, v5
	v_and_b32_e32 v35, 0xffff0000, v15
	v_add_f32_e32 v5, 1.0, v5
	v_rcp_f32_e32 v36, v5
	v_pk_mul_f32 v[32:33], v[32:33], v[4:5] op_sel_hi:[1,0]
	v_mul_f32_e32 v5, 0xbfb8aa3b, v35
	v_exp_f32_e32 v5, v5
	v_pk_mul_f32 v[32:33], v[38:39], v[32:33]
	v_add_f32_e32 v5, 1.0, v5
	v_rcp_f32_e32 v37, v5
	s_nop 0
	v_pk_mul_f32 v[34:35], v[36:37], v[34:35]
	s_nop 0
	v_pk_mul_f32 v[32:33], v[32:33], v[34:35]
	s_nop 0
	v_cvt_pk_bf16_f32 v15, v32, v33
	global_store_dwordx2 v[12:13], v[14:15], off offset:64
	s_nop 0
	s_waitcnt vmcnt(11)
; __device__ __forceinline__ unsigned pk2(float lo, float hi) { return pg8::cvtpk(lo, hi); }
; __device__ __forceinline__ float silu_f(float v) { return v * __builtin_amdgcn_rcpf(1.0f + __expf(-v)); }
; __device__ __forceinline__ void gla_inter_unit(const Params& P, LAS unsigned char* lds, int unit) {
;     ...
;     for (int vbi = 0; vbi < 8; ++vbi) { const int vcol = 16 * (vh * 8 + vbi) + 4 * fq;
;         const f32x4 g = *(const f32x4*)(P.g_gla + vcol); const u32x2 rw = *(const u32x2*)(Z + trow * ZC + ZO_RG + 256 * h + vcol);
;         const float r0 = __uint_as_float(rw.x << 16), r1 = __uint_as_float(rw.x & 0xffff0000u), r2 = __uint_as_float(rw.y << 16), r3 = __uint_as_float(rw.y & 0xffff0000u);
;         u32x2 w; w.x = pk2(o[vbi][0] * rstd * g[0] * silu_f(r0), o[vbi][1] * rstd * g[1] * silu_f(r1)); w.y = pk2(o[vbi][2] * rstd * g[2] * silu_f(r2), o[vbi][3] * rstd * g[3] * silu_f(r3));
;         *(u32x2*)(AO + trow * DM + 1024 + 256 * h + vcol) = w; }
;     __syncthreads();
	v_mov_b32_e32 v32, v72
	v_mov_b32_e32 v33, v73
	v_mov_b32_e32 v34, v74
	v_mov_b32_e32 v35, v75
	v_mov_b32_e32 v14, v98
	v_mov_b32_e32 v15, v99
	v_lshlrev_b32_e32 v36, 16, v14
	v_mul_f32_e32 v5, 0xbfb8aa3b, v36
	v_exp_f32_e32 v5, v5
	v_and_b32_e32 v37, 0xffff0000, v14
	v_add_f32_e32 v5, 1.0, v5
	v_rcp_f32_e32 v38, v5
	v_pk_mul_f32 v[30:31], v[30:31], v[4:5] op_sel_hi:[1,0]
	v_mul_f32_e32 v5, 0xbfb8aa3b, v37
	v_exp_f32_e32 v5, v5
	v_pk_mul_f32 v[30:31], v[30:31], v[32:33]
	v_add_f32_e32 v5, 1.0, v5
	v_rcp_f32_e32 v39, v5
	s_nop 0
	v_pk_mul_f32 v[32:33], v[38:39], v[36:37]
	s_nop 0
	v_pk_mul_f32 v[30:31], v[30:31], v[32:33]
	s_nop 0
	v_cvt_pk_bf16_f32 v14, v30, v31
	v_lshlrev_b32_e32 v30, 16, v15
	v_mul_f32_e32 v5, 0xbfb8aa3b, v30
	v_exp_f32_e32 v5, v5
	v_and_b32_e32 v31, 0xffff0000, v15
	v_add_f32_e32 v5, 1.0, v5
	v_rcp_f32_e32 v32, v5
	v_pk_mul_f32 v[28:29], v[28:29], v[4:5] op_sel_hi:[1,0]
	v_mul_f32_e32 v5, 0xbfb8aa3b, v31
	v_exp_f32_e32 v5, v5
	v_pk_mul_f32 v[28:29], v[28:29], v[34:35]
	v_add_f32_e32 v5, 1.0, v5
	v_rcp_f32_e32 v33, v5
	s_nop 0
	v_pk_mul_f32 v[30:31], v[32:33], v[30:31]
	s_nop 0
	v_pk_mul_f32 v[28:29], v[28:29], v[30:31]
	s_nop 0
	v_cvt_pk_bf16_f32 v15, v28, v29
	global_store_dwordx2 v[12:13], v[14:15], off offset:96
	s_nop 0
	s_waitcnt vmcnt(10)
	v_mov_b32_e32 v28, v76
	v_mov_b32_e32 v29, v77
	v_mov_b32_e32 v30, v78
	v_mov_b32_e32 v31, v79
	v_mov_b32_e32 v14, v100
	v_mov_b32_e32 v15, v101
	v_lshlrev_b32_e32 v32, 16, v14
	v_mul_f32_e32 v5, 0xbfb8aa3b, v32
	v_exp_f32_e32 v5, v5
	v_and_b32_e32 v33, 0xffff0000, v14
	v_add_f32_e32 v5, 1.0, v5
	v_rcp_f32_e32 v34, v5
	v_pk_mul_f32 v[26:27], v[26:27], v[4:5] op_sel_hi:[1,0]
	v_mul_f32_e32 v5, 0xbfb8aa3b, v33
	v_exp_f32_e32 v5, v5
	v_pk_mul_f32 v[26:27], v[26:27], v[28:29]
	v_add_f32_e32 v5, 1.0, v5
	v_rcp_f32_e32 v35, v5
	s_nop 0
	v_pk_mul_f32 v[28:29], v[34:35], v[32:33]
	s_nop 0
	v_pk_mul_f32 v[26:27], v[26:27], v[28:29]
	s_nop 0
	v_cvt_pk_bf16_f32 v14, v26, v27
	v_lshlrev_b32_e32 v26, 16, v15
	v_mul_f32_e32 v5, 0xbfb8aa3b, v26
	v_exp_f32_e32 v5, v5
	v_and_b32_e32 v27, 0xffff0000, v15
	v_add_f32_e32 v5, 1.0, v5
	v_rcp_f32_e32 v28, v5
	v_pk_mul_f32 v[24:25], v[24:25], v[4:5] op_sel_hi:[1,0]
	v_mul_f32_e32 v5, 0xbfb8aa3b, v27
	v_exp_f32_e32 v5, v5
	v_pk_mul_f32 v[24:25], v[24:25], v[30:31]
	v_add_f32_e32 v5, 1.0, v5
	v_rcp_f32_e32 v29, v5
	s_nop 0
	v_pk_mul_f32 v[26:27], v[28:29], v[26:27]
	s_nop 0
	v_pk_mul_f32 v[24:25], v[24:25], v[26:27]
	s_nop 0
	v_cvt_pk_bf16_f32 v15, v24, v25
	global_store_dwordx2 v[12:13], v[14:15], off offset:128
	s_nop 0
	s_waitcnt vmcnt(9)
	v_mov_b32_e32 v24, v80
	v_mov_b32_e32 v25, v81
	v_mov_b32_e32 v26, v82
	v_mov_b32_e32 v27, v83
	v_mov_b32_e32 v14, v102
	v_mov_b32_e32 v15, v103
	v_lshlrev_b32_e32 v28, 16, v14
	v_mul_f32_e32 v5, 0xbfb8aa3b, v28
	v_exp_f32_e32 v5, v5
	v_and_b32_e32 v29, 0xffff0000, v14
	v_add_f32_e32 v5, 1.0, v5
	v_rcp_f32_e32 v30, v5
	v_pk_mul_f32 v[22:23], v[22:23], v[4:5] op_sel_hi:[1,0]
	v_mul_f32_e32 v5, 0xbfb8aa3b, v29
	v_exp_f32_e32 v5, v5
	v_pk_mul_f32 v[22:23], v[22:23], v[24:25]
	v_add_f32_e32 v5, 1.0, v5
	v_rcp_f32_e32 v31, v5
	s_nop 0
	v_pk_mul_f32 v[24:25], v[30:31], v[28:29]
	s_nop 0
	v_pk_mul_f32 v[22:23], v[22:23], v[24:25]
	s_nop 0
	v_cvt_pk_bf16_f32 v14, v22, v23
	v_lshlrev_b32_e32 v22, 16, v15
	v_mul_f32_e32 v5, 0xbfb8aa3b, v22
	v_exp_f32_e32 v5, v5
	v_and_b32_e32 v23, 0xffff0000, v15
	v_add_f32_e32 v5, 1.0, v5
	v_rcp_f32_e32 v24, v5
	v_pk_mul_f32 v[20:21], v[20:21], v[4:5] op_sel_hi:[1,0]
	v_mul_f32_e32 v5, 0xbfb8aa3b, v23
	v_exp_f32_e32 v5, v5
	v_pk_mul_f32 v[20:21], v[20:21], v[26:27]
	v_add_f32_e32 v5, 1.0, v5
	v_rcp_f32_e32 v25, v5
	s_nop 0
	v_pk_mul_f32 v[22:23], v[24:25], v[22:23]
	s_nop 0
	v_pk_mul_f32 v[20:21], v[20:21], v[22:23]
	s_nop 0
	v_cvt_pk_bf16_f32 v15, v20, v21
	global_store_dwordx2 v[12:13], v[14:15], off offset:160
	s_nop 0
	s_waitcnt vmcnt(8)
	v_mov_b32_e32 v20, v84
	v_mov_b32_e32 v21, v85
	v_mov_b32_e32 v22, v86
	v_mov_b32_e32 v23, v87
	v_mov_b32_e32 v14, v104
	v_mov_b32_e32 v15, v105
	v_lshlrev_b32_e32 v24, 16, v14
	v_mul_f32_e32 v5, 0xbfb8aa3b, v24
	v_exp_f32_e32 v5, v5
	v_and_b32_e32 v25, 0xffff0000, v14
	v_add_f32_e32 v5, 1.0, v5
	v_rcp_f32_e32 v26, v5
	v_pk_mul_f32 v[18:19], v[18:19], v[4:5] op_sel_hi:[1,0]
	v_mul_f32_e32 v5, 0xbfb8aa3b, v25
	v_exp_f32_e32 v5, v5
	v_pk_mul_f32 v[18:19], v[18:19], v[20:21]
	v_add_f32_e32 v5, 1.0, v5
	v_rcp_f32_e32 v27, v5
	s_nop 0
	v_pk_mul_f32 v[20:21], v[26:27], v[24:25]
	s_nop 0
	v_pk_mul_f32 v[18:19], v[18:19], v[20:21]
	s_nop 0
	v_cvt_pk_bf16_f32 v14, v18, v19
	v_lshlrev_b32_e32 v18, 16, v15
	v_mul_f32_e32 v5, 0xbfb8aa3b, v18
	v_exp_f32_e32 v5, v5
	v_and_b32_e32 v19, 0xffff0000, v15
	v_add_f32_e32 v5, 1.0, v5
	v_rcp_f32_e32 v20, v5
	v_pk_mul_f32 v[6:7], v[6:7], v[4:5] op_sel_hi:[1,0]
	v_mul_f32_e32 v5, 0xbfb8aa3b, v19
	v_exp_f32_e32 v5, v5
	v_pk_mul_f32 v[6:7], v[6:7], v[22:23]
	v_add_f32_e32 v5, 1.0, v5
	v_rcp_f32_e32 v21, v5
	s_nop 0
	v_pk_mul_f32 v[18:19], v[20:21], v[18:19]
	s_nop 0
	v_pk_mul_f32 v[6:7], v[6:7], v[18:19]
	s_nop 0
	v_cvt_pk_bf16_f32 v15, v6, v7
	global_store_dwordx2 v[12:13], v[14:15], off offset:192
	s_nop 0
	s_waitcnt vmcnt(7)
	v_mov_b32_e32 v6, v88
	v_mov_b32_e32 v7, v89
	v_mov_b32_e32 v8, v90
	v_mov_b32_e32 v9, v91
	v_mov_b32_e32 v10, v106
	v_mov_b32_e32 v11, v107
	v_lshlrev_b32_e32 v14, 16, v10
	v_mul_f32_e32 v5, 0xbfb8aa3b, v14
	v_exp_f32_e32 v5, v5
	v_and_b32_e32 v15, 0xffff0000, v10
	v_add_f32_e32 v5, 1.0, v5
	v_rcp_f32_e32 v18, v5
	v_pk_mul_f32 v[2:3], v[2:3], v[4:5] op_sel_hi:[1,0]
	v_mul_f32_e32 v5, 0xbfb8aa3b, v15
	v_exp_f32_e32 v5, v5
	v_pk_mul_f32 v[2:3], v[2:3], v[6:7]
	v_add_f32_e32 v5, 1.0, v5
	v_rcp_f32_e32 v19, v5
	v_pk_mul_f32 v[0:1], v[0:1], v[4:5] op_sel_hi:[1,0]
	v_pk_mul_f32 v[6:7], v[18:19], v[14:15]
	s_nop 0
	v_pk_mul_f32 v[2:3], v[2:3], v[6:7]
	v_lshlrev_b32_e32 v6, 16, v11
	v_cvt_pk_bf16_f32 v2, v2, v3
	v_mul_f32_e32 v3, 0xbfb8aa3b, v6
	v_exp_f32_e32 v3, v3
	v_and_b32_e32 v7, 0xffff0000, v11
	v_pk_mul_f32 v[0:1], v[0:1], v[8:9]
	v_add_f32_e32 v3, 1.0, v3
	v_rcp_f32_e32 v10, v3
	v_mul_f32_e32 v3, 0xbfb8aa3b, v7
	v_exp_f32_e32 v3, v3
	s_nop 0
	v_add_f32_e32 v3, 1.0, v3
	v_rcp_f32_e32 v11, v3
	s_nop 0
	v_pk_mul_f32 v[4:5], v[10:11], v[6:7]
	s_nop 0
	v_pk_mul_f32 v[0:1], v[0:1], v[4:5]
	s_nop 0
	v_cvt_pk_bf16_f32 v3, v0, v1
	global_store_dwordx2 v[12:13], v[2:3], off offset:224
	s_barrier
	s_cbranch_scc1 .LBB0_545
